# v50: v49 + passB n.q dot fully unrolled, double-buffered LDS reads, packed f32 FMA accumulators (both units)
# baseline (speedup 1.0000x reference)
; #define LAS __attribute__((address_space(3)))
; __device__ __forceinline__ float bf_lo(unsigned w) { return __uint_as_float(w << 16); }
; __device__ __forceinline__ float bf_hi(unsigned w) { return __uint_as_float(w & 0xffff0000u); }
; __device__ void passB_unit(const Params& p, LAS unsigned char* lds, int u, bool do_store = true) {
;     ...
;     if (tid < 256) { const int d = tid >> 7, t = sc_t; if (wid & 1) sc_pm = fmaxf(sc_pm, wmax[wid - 1]);
;         const float mc = ((const float*)(p.ws + OFF_MST))[(sid0 + d) * 16 + c];
;         const float Mt = fmaxf(mc, sc_pm); const int dt = d * 128 + t;
;         aA[dt] = sc_a; MA[dt] = Mt; winA[dt] = expf(mc - Mt); clampA[dt] = expf(-(sc_b + Mt));
;         float s = 0.f; const LAS float* nv = nvec + d * 256;
; #pragma unroll 4
;         for (int k8 = 0; k8 < 32; ++k8) { const u32x4 qv = *(const LAS u32x4*)(Qs + t * 264 + k8 * 8); const LAS float* np = nv + k8 * 8;
;             s += bf_lo(qv.x) * np[0] + bf_hi(qv.x) * np[1] + bf_lo(qv.y) * np[2] + bf_hi(qv.y) * np[3] + bf_lo(qv.z) * np[4] + bf_hi(qv.z) * np[5] + bf_lo(qv.w) * np[6] + bf_hi(qv.w) * np[7]; }
;         nqA[dt] = s; }
.LBB0_546:
	s_or_b64 exec, exec, s[6:7]
	v_ashrrev_i32_e32 v71, 7, v196
	v_add_u32_e32 v60, s50, v71
	v_lshl_or_b32 v72, v60, 4, s52
	v_ashrrev_i32_e32 v73, 31, v72
	v_lshl_add_u64 v[72:73], v[72:73], 2, s[14:15]
	global_load_dword v72, v[72:73], off
	v_max_f32_e32 v70, v70, v70
	s_mov_b32 s10, 0x3fb8aa3b
	s_mov_b32 s25, 0xbfb8aa3b
	s_movk_i32 s7, 0xff80
	s_movk_i32 s29, 0x210
	v_and_or_b32 v74, v196, s7, v63
	v_mad_i32_i24 v68, v63, s29, 0
	v_lshl_add_u32 v63, v74, 2, 0
	s_mov_b32 s11, 0xc2ce8ed0
	v_add_u32_e32 v74, 0x22000, v63
	s_mov_b32 s26, 0x42ce8ed0
	v_add_u32_e32 v75, 0x22400, v63
	s_mov_b32 s24, 0x42b17218
	v_mov_b32_e32 v73, 0x7f800000
	s_mov_b32 s28, 0xc2b17218
	v_add_u32_e32 v76, 0x22800, v63
	s_mov_b32 s6, 0
	v_mov_b32_e32 v60, 0
	v_add_u32_e32 v77, 0x22c00, v63
	s_waitcnt vmcnt(0)
	v_max_f32_e32 v78, v72, v72
	v_max_f32_e32 v70, v78, v70
	v_sub_f32_e32 v72, v72, v70
	v_add_f32_e32 v69, v69, v70
	v_mul_f32_e32 v78, 0x3fb8aa3b, v72
	v_mul_f32_e32 v79, 0xbfb8aa3b, v69
	v_fma_f32 v80, v72, s10, -v78
	v_rndne_f32_e32 v81, v78
	v_fma_f32 v82, v69, s25, -v79
	v_rndne_f32_e32 v83, v79
	v_fmamk_f32 v80, v72, 0x32a5705f, v80
	v_sub_f32_e32 v78, v78, v81
	v_fmamk_f32 v82, v69, 0xb2a5705f, v82
	v_sub_f32_e32 v79, v79, v83
	v_add_f32_e32 v78, v78, v80
	v_cvt_i32_f32_e32 v81, v81
	v_add_f32_e32 v79, v79, v82
	v_exp_f32_e32 v78, v78
	v_cvt_i32_f32_e32 v83, v83
	v_exp_f32_e32 v79, v79
	ds_write_b32 v74, v61
	ds_write_b32 v75, v70
	v_ldexp_f32 v61, v78, v81
	v_cmp_ngt_f32_e32 vcc, s11, v72
	v_ldexp_f32 v70, v79, v83
	s_nop 0
	v_cndmask_b32_e32 v61, 0, v61, vcc
	v_cmp_nlt_f32_e32 vcc, s26, v69
	s_nop 1
	v_cndmask_b32_e32 v70, 0, v70, vcc
	v_cmp_nlt_f32_e32 vcc, s24, v72
	s_nop 1
	v_cndmask_b32_e32 v61, v73, v61, vcc
	v_cmp_ngt_f32_e32 vcc, s28, v69
	s_nop 1
	v_cndmask_b32_e32 v69, v73, v70, vcc
	ds_write_b32 v76, v61
	ds_write_b32 v77, v69
	v_lshl_add_u32 v61, v71, 10, 0
	v_add_u32_e32 v69, 0x23400, v61
	s_mov_b32 s7, 0xffff0000
	ds_read_b128 v[70:73], v68 offset:0
	ds_read_b128 v[94:97], v69 offset:0
	ds_read_b128 v[98:101], v69 offset:16
	ds_read_b128 v[74:77], v68 offset:16
	ds_read_b128 v[102:105], v69 offset:32
	ds_read_b128 v[106:109], v69 offset:48
	ds_read_b128 v[78:81], v68 offset:32
	ds_read_b128 v[110:113], v69 offset:64
	ds_read_b128 v[114:117], v69 offset:80
	ds_read_b128 v[82:85], v68 offset:48
	ds_read_b128 v[118:121], v69 offset:96
	ds_read_b128 v[122:125], v69 offset:112
	ds_read_b128 v[142:145], v68 offset:64
	ds_read_b128 v[160:163], v69 offset:128
	ds_read_b128 v[164:167], v69 offset:144
	ds_read_b128 v[146:149], v68 offset:80
	ds_read_b128 v[168:171], v69 offset:160
	ds_read_b128 v[172:175], v69 offset:176
	ds_read_b128 v[150:153], v68 offset:96
	ds_read_b128 v[176:179], v69 offset:192
	ds_read_b128 v[180:183], v69 offset:208
	ds_read_b128 v[154:157], v68 offset:112
	ds_read_b128 v[184:187], v69 offset:224
	ds_read_b128 v[188:191], v69 offset:240
	s_waitcnt lgkmcnt(15)
	v_lshlrev_b32_e32 v126, 16, v70
	v_and_b32_e32 v127, s7, v70
	v_pk_mul_f32 v[86:87], v[94:95], v[126:127]
	v_lshlrev_b32_e32 v128, 16, v71
	v_and_b32_e32 v129, s7, v71
	v_pk_mul_f32 v[192:193], v[96:97], v[128:129]
	v_lshlrev_b32_e32 v130, 16, v72
	v_and_b32_e32 v131, s7, v72
	v_pk_mul_f32 v[194:195], v[98:99], v[130:131]
	v_lshlrev_b32_e32 v132, 16, v73
	v_and_b32_e32 v133, s7, v73
	v_pk_mul_f32 v[204:205], v[100:101], v[132:133]
	s_waitcnt lgkmcnt(15)
	v_lshlrev_b32_e32 v134, 16, v74
	v_and_b32_e32 v135, s7, v74
	v_pk_fma_f32 v[86:87], v[102:103], v[134:135], v[86:87]
	v_lshlrev_b32_e32 v136, 16, v75
	v_and_b32_e32 v137, s7, v75
	v_pk_fma_f32 v[192:193], v[104:105], v[136:137], v[192:193]
	v_lshlrev_b32_e32 v138, 16, v76
	v_and_b32_e32 v139, s7, v76
	v_pk_fma_f32 v[194:195], v[106:107], v[138:139], v[194:195]
	v_lshlrev_b32_e32 v140, 16, v77
	v_and_b32_e32 v141, s7, v77
	v_pk_fma_f32 v[204:205], v[108:109], v[140:141], v[204:205]
	s_waitcnt lgkmcnt(15)
	v_lshlrev_b32_e32 v126, 16, v78
	v_and_b32_e32 v127, s7, v78
	v_pk_fma_f32 v[86:87], v[110:111], v[126:127], v[86:87]
	v_lshlrev_b32_e32 v128, 16, v79
	v_and_b32_e32 v129, s7, v79
	v_pk_fma_f32 v[192:193], v[112:113], v[128:129], v[192:193]
	v_lshlrev_b32_e32 v130, 16, v80
	v_and_b32_e32 v131, s7, v80
	v_pk_fma_f32 v[194:195], v[114:115], v[130:131], v[194:195]
	v_lshlrev_b32_e32 v132, 16, v81
	v_and_b32_e32 v133, s7, v81
	v_pk_fma_f32 v[204:205], v[116:117], v[132:133], v[204:205]
	s_waitcnt lgkmcnt(12)
	v_lshlrev_b32_e32 v134, 16, v82
	v_and_b32_e32 v135, s7, v82
	v_pk_fma_f32 v[86:87], v[118:119], v[134:135], v[86:87]
	v_lshlrev_b32_e32 v136, 16, v83
	v_and_b32_e32 v137, s7, v83
	v_pk_fma_f32 v[192:193], v[120:121], v[136:137], v[192:193]
	v_lshlrev_b32_e32 v138, 16, v84
	v_and_b32_e32 v139, s7, v84
	v_pk_fma_f32 v[194:195], v[122:123], v[138:139], v[194:195]
	v_lshlrev_b32_e32 v140, 16, v85
	v_and_b32_e32 v141, s7, v85
	v_pk_fma_f32 v[204:205], v[124:125], v[140:141], v[204:205]
	ds_read_b128 v[70:73], v68 offset:128
	ds_read_b128 v[94:97], v69 offset:256
	ds_read_b128 v[98:101], v69 offset:272
	ds_read_b128 v[74:77], v68 offset:144
	ds_read_b128 v[102:105], v69 offset:288
	ds_read_b128 v[106:109], v69 offset:304
	ds_read_b128 v[78:81], v68 offset:160
	ds_read_b128 v[110:113], v69 offset:320
	ds_read_b128 v[114:117], v69 offset:336
	ds_read_b128 v[82:85], v68 offset:176
	ds_read_b128 v[118:121], v69 offset:352
	ds_read_b128 v[122:125], v69 offset:368
	s_waitcnt lgkmcnt(15)
; #define LAS __attribute__((address_space(3)))
; __device__ __forceinline__ float bf_lo(unsigned w) { return __uint_as_float(w << 16); }
; __device__ __forceinline__ float bf_hi(unsigned w) { return __uint_as_float(w & 0xffff0000u); }
; __device__ void passB_unit(const Params& p, LAS unsigned char* lds, int u, bool do_store = true) {
;     ...
;         for (int k8 = 0; k8 < 32; ++k8) { const u32x4 qv = *(const LAS u32x4*)(Qs + t * 264 + k8 * 8); const LAS float* np = nv + k8 * 8;
;             s += bf_lo(qv.x) * np[0] + bf_hi(qv.x) * np[1] + bf_lo(qv.y) * np[2] + bf_hi(qv.y) * np[3] + bf_lo(qv.z) * np[4] + bf_hi(qv.z) * np[5] + bf_lo(qv.w) * np[6] + bf_hi(qv.w) * np[7]; }
	v_lshlrev_b32_e32 v126, 16, v142
	v_and_b32_e32 v127, s7, v142
	v_pk_fma_f32 v[86:87], v[160:161], v[126:127], v[86:87]
	v_lshlrev_b32_e32 v128, 16, v143
	v_and_b32_e32 v129, s7, v143
	v_pk_fma_f32 v[192:193], v[162:163], v[128:129], v[192:193]
	v_lshlrev_b32_e32 v130, 16, v144
	v_and_b32_e32 v131, s7, v144
	v_pk_fma_f32 v[194:195], v[164:165], v[130:131], v[194:195]
	v_lshlrev_b32_e32 v132, 16, v145
	v_and_b32_e32 v133, s7, v145
	v_pk_fma_f32 v[204:205], v[166:167], v[132:133], v[204:205]
	s_waitcnt lgkmcnt(15)
	v_lshlrev_b32_e32 v134, 16, v146
	v_and_b32_e32 v135, s7, v146
	v_pk_fma_f32 v[86:87], v[168:169], v[134:135], v[86:87]
	v_lshlrev_b32_e32 v136, 16, v147
	v_and_b32_e32 v137, s7, v147
	v_pk_fma_f32 v[192:193], v[170:171], v[136:137], v[192:193]
	v_lshlrev_b32_e32 v138, 16, v148
	v_and_b32_e32 v139, s7, v148
	v_pk_fma_f32 v[194:195], v[172:173], v[138:139], v[194:195]
	v_lshlrev_b32_e32 v140, 16, v149
	v_and_b32_e32 v141, s7, v149
	v_pk_fma_f32 v[204:205], v[174:175], v[140:141], v[204:205]
	s_waitcnt lgkmcnt(15)
	v_lshlrev_b32_e32 v126, 16, v150
	v_and_b32_e32 v127, s7, v150
	v_pk_fma_f32 v[86:87], v[176:177], v[126:127], v[86:87]
	v_lshlrev_b32_e32 v128, 16, v151
	v_and_b32_e32 v129, s7, v151
	v_pk_fma_f32 v[192:193], v[178:179], v[128:129], v[192:193]
	v_lshlrev_b32_e32 v130, 16, v152
	v_and_b32_e32 v131, s7, v152
	v_pk_fma_f32 v[194:195], v[180:181], v[130:131], v[194:195]
	v_lshlrev_b32_e32 v132, 16, v153
	v_and_b32_e32 v133, s7, v153
	v_pk_fma_f32 v[204:205], v[182:183], v[132:133], v[204:205]
	s_waitcnt lgkmcnt(12)
	v_lshlrev_b32_e32 v134, 16, v154
	v_and_b32_e32 v135, s7, v154
	v_pk_fma_f32 v[86:87], v[184:185], v[134:135], v[86:87]
	v_lshlrev_b32_e32 v136, 16, v155
	v_and_b32_e32 v137, s7, v155
	v_pk_fma_f32 v[192:193], v[186:187], v[136:137], v[192:193]
	v_lshlrev_b32_e32 v138, 16, v156
	v_and_b32_e32 v139, s7, v156
	v_pk_fma_f32 v[194:195], v[188:189], v[138:139], v[194:195]
	v_lshlrev_b32_e32 v140, 16, v157
	v_and_b32_e32 v141, s7, v157
	v_pk_fma_f32 v[204:205], v[190:191], v[140:141], v[204:205]
	ds_read_b128 v[142:145], v68 offset:192
	ds_read_b128 v[160:163], v69 offset:384
	ds_read_b128 v[164:167], v69 offset:400
	ds_read_b128 v[146:149], v68 offset:208
	ds_read_b128 v[168:171], v69 offset:416
	ds_read_b128 v[172:175], v69 offset:432
	ds_read_b128 v[150:153], v68 offset:224
	ds_read_b128 v[176:179], v69 offset:448
	ds_read_b128 v[180:183], v69 offset:464
	ds_read_b128 v[154:157], v68 offset:240
	ds_read_b128 v[184:187], v69 offset:480
	ds_read_b128 v[188:191], v69 offset:496
	s_waitcnt lgkmcnt(15)
	v_lshlrev_b32_e32 v126, 16, v70
	v_and_b32_e32 v127, s7, v70
	v_pk_fma_f32 v[86:87], v[94:95], v[126:127], v[86:87]
	v_lshlrev_b32_e32 v128, 16, v71
	v_and_b32_e32 v129, s7, v71
	v_pk_fma_f32 v[192:193], v[96:97], v[128:129], v[192:193]
	v_lshlrev_b32_e32 v130, 16, v72
	v_and_b32_e32 v131, s7, v72
	v_pk_fma_f32 v[194:195], v[98:99], v[130:131], v[194:195]
	v_lshlrev_b32_e32 v132, 16, v73
	v_and_b32_e32 v133, s7, v73
	v_pk_fma_f32 v[204:205], v[100:101], v[132:133], v[204:205]
	s_waitcnt lgkmcnt(15)
	v_lshlrev_b32_e32 v134, 16, v74
	v_and_b32_e32 v135, s7, v74
	v_pk_fma_f32 v[86:87], v[102:103], v[134:135], v[86:87]
	v_lshlrev_b32_e32 v136, 16, v75
	v_and_b32_e32 v137, s7, v75
	v_pk_fma_f32 v[192:193], v[104:105], v[136:137], v[192:193]
	v_lshlrev_b32_e32 v138, 16, v76
	v_and_b32_e32 v139, s7, v76
	v_pk_fma_f32 v[194:195], v[106:107], v[138:139], v[194:195]
	v_lshlrev_b32_e32 v140, 16, v77
	v_and_b32_e32 v141, s7, v77
	v_pk_fma_f32 v[204:205], v[108:109], v[140:141], v[204:205]
	s_waitcnt lgkmcnt(15)
	v_lshlrev_b32_e32 v126, 16, v78
	v_and_b32_e32 v127, s7, v78
	v_pk_fma_f32 v[86:87], v[110:111], v[126:127], v[86:87]
	v_lshlrev_b32_e32 v128, 16, v79
	v_and_b32_e32 v129, s7, v79
	v_pk_fma_f32 v[192:193], v[112:113], v[128:129], v[192:193]
	v_lshlrev_b32_e32 v130, 16, v80
	v_and_b32_e32 v131, s7, v80
	v_pk_fma_f32 v[194:195], v[114:115], v[130:131], v[194:195]
	v_lshlrev_b32_e32 v132, 16, v81
	v_and_b32_e32 v133, s7, v81
	v_pk_fma_f32 v[204:205], v[116:117], v[132:133], v[204:205]
	s_waitcnt lgkmcnt(12)
	v_lshlrev_b32_e32 v134, 16, v82
	v_and_b32_e32 v135, s7, v82
	v_pk_fma_f32 v[86:87], v[118:119], v[134:135], v[86:87]
	v_lshlrev_b32_e32 v136, 16, v83
	v_and_b32_e32 v137, s7, v83
	v_pk_fma_f32 v[192:193], v[120:121], v[136:137], v[192:193]
	v_lshlrev_b32_e32 v138, 16, v84
	v_and_b32_e32 v139, s7, v84
	v_pk_fma_f32 v[194:195], v[122:123], v[138:139], v[194:195]
	v_lshlrev_b32_e32 v140, 16, v85
	v_and_b32_e32 v141, s7, v85
	v_pk_fma_f32 v[204:205], v[124:125], v[140:141], v[204:205]
	ds_read_b128 v[70:73], v68 offset:256
	ds_read_b128 v[94:97], v69 offset:512
	ds_read_b128 v[98:101], v69 offset:528
	ds_read_b128 v[74:77], v68 offset:272
	ds_read_b128 v[102:105], v69 offset:544
	ds_read_b128 v[106:109], v69 offset:560
	ds_read_b128 v[78:81], v68 offset:288
	ds_read_b128 v[110:113], v69 offset:576
	ds_read_b128 v[114:117], v69 offset:592
	ds_read_b128 v[82:85], v68 offset:304
	ds_read_b128 v[118:121], v69 offset:608
	ds_read_b128 v[122:125], v69 offset:624
	s_waitcnt lgkmcnt(15)
	v_lshlrev_b32_e32 v126, 16, v142
	v_and_b32_e32 v127, s7, v142
	v_pk_fma_f32 v[86:87], v[160:161], v[126:127], v[86:87]
	v_lshlrev_b32_e32 v128, 16, v143
	v_and_b32_e32 v129, s7, v143
	v_pk_fma_f32 v[192:193], v[162:163], v[128:129], v[192:193]
	v_lshlrev_b32_e32 v130, 16, v144
	v_and_b32_e32 v131, s7, v144
	v_pk_fma_f32 v[194:195], v[164:165], v[130:131], v[194:195]
	v_lshlrev_b32_e32 v132, 16, v145
	v_and_b32_e32 v133, s7, v145
	v_pk_fma_f32 v[204:205], v[166:167], v[132:133], v[204:205]
	s_waitcnt lgkmcnt(15)
; #define LAS __attribute__((address_space(3)))
; __device__ __forceinline__ float bf_lo(unsigned w) { return __uint_as_float(w << 16); }
; __device__ __forceinline__ float bf_hi(unsigned w) { return __uint_as_float(w & 0xffff0000u); }
; __device__ void passB_unit(const Params& p, LAS unsigned char* lds, int u, bool do_store = true) {
;     ...
;         for (int k8 = 0; k8 < 32; ++k8) { const u32x4 qv = *(const LAS u32x4*)(Qs + t * 264 + k8 * 8); const LAS float* np = nv + k8 * 8;
;             s += bf_lo(qv.x) * np[0] + bf_hi(qv.x) * np[1] + bf_lo(qv.y) * np[2] + bf_hi(qv.y) * np[3] + bf_lo(qv.z) * np[4] + bf_hi(qv.z) * np[5] + bf_lo(qv.w) * np[6] + bf_hi(qv.w) * np[7]; }
	v_lshlrev_b32_e32 v134, 16, v146
	v_and_b32_e32 v135, s7, v146
	v_pk_fma_f32 v[86:87], v[168:169], v[134:135], v[86:87]
	v_lshlrev_b32_e32 v136, 16, v147
	v_and_b32_e32 v137, s7, v147
	v_pk_fma_f32 v[192:193], v[170:171], v[136:137], v[192:193]
	v_lshlrev_b32_e32 v138, 16, v148
	v_and_b32_e32 v139, s7, v148
	v_pk_fma_f32 v[194:195], v[172:173], v[138:139], v[194:195]
	v_lshlrev_b32_e32 v140, 16, v149
	v_and_b32_e32 v141, s7, v149
	v_pk_fma_f32 v[204:205], v[174:175], v[140:141], v[204:205]
	s_waitcnt lgkmcnt(15)
	v_lshlrev_b32_e32 v126, 16, v150
	v_and_b32_e32 v127, s7, v150
	v_pk_fma_f32 v[86:87], v[176:177], v[126:127], v[86:87]
	v_lshlrev_b32_e32 v128, 16, v151
	v_and_b32_e32 v129, s7, v151
	v_pk_fma_f32 v[192:193], v[178:179], v[128:129], v[192:193]
	v_lshlrev_b32_e32 v130, 16, v152
	v_and_b32_e32 v131, s7, v152
	v_pk_fma_f32 v[194:195], v[180:181], v[130:131], v[194:195]
	v_lshlrev_b32_e32 v132, 16, v153
	v_and_b32_e32 v133, s7, v153
	v_pk_fma_f32 v[204:205], v[182:183], v[132:133], v[204:205]
	s_waitcnt lgkmcnt(12)
	v_lshlrev_b32_e32 v134, 16, v154
	v_and_b32_e32 v135, s7, v154
	v_pk_fma_f32 v[86:87], v[184:185], v[134:135], v[86:87]
	v_lshlrev_b32_e32 v136, 16, v155
	v_and_b32_e32 v137, s7, v155
	v_pk_fma_f32 v[192:193], v[186:187], v[136:137], v[192:193]
	v_lshlrev_b32_e32 v138, 16, v156
	v_and_b32_e32 v139, s7, v156
	v_pk_fma_f32 v[194:195], v[188:189], v[138:139], v[194:195]
	v_lshlrev_b32_e32 v140, 16, v157
	v_and_b32_e32 v141, s7, v157
	v_pk_fma_f32 v[204:205], v[190:191], v[140:141], v[204:205]
	ds_read_b128 v[142:145], v68 offset:320
	ds_read_b128 v[160:163], v69 offset:640
	ds_read_b128 v[164:167], v69 offset:656
	ds_read_b128 v[146:149], v68 offset:336
	ds_read_b128 v[168:171], v69 offset:672
	ds_read_b128 v[172:175], v69 offset:688
	ds_read_b128 v[150:153], v68 offset:352
	ds_read_b128 v[176:179], v69 offset:704
	ds_read_b128 v[180:183], v69 offset:720
	ds_read_b128 v[154:157], v68 offset:368
	ds_read_b128 v[184:187], v69 offset:736
	ds_read_b128 v[188:191], v69 offset:752
	s_waitcnt lgkmcnt(15)
	v_lshlrev_b32_e32 v126, 16, v70
	v_and_b32_e32 v127, s7, v70
	v_pk_fma_f32 v[86:87], v[94:95], v[126:127], v[86:87]
	v_lshlrev_b32_e32 v128, 16, v71
	v_and_b32_e32 v129, s7, v71
	v_pk_fma_f32 v[192:193], v[96:97], v[128:129], v[192:193]
	v_lshlrev_b32_e32 v130, 16, v72
	v_and_b32_e32 v131, s7, v72
	v_pk_fma_f32 v[194:195], v[98:99], v[130:131], v[194:195]
	v_lshlrev_b32_e32 v132, 16, v73
	v_and_b32_e32 v133, s7, v73
	v_pk_fma_f32 v[204:205], v[100:101], v[132:133], v[204:205]
	s_waitcnt lgkmcnt(15)
	v_lshlrev_b32_e32 v134, 16, v74
	v_and_b32_e32 v135, s7, v74
	v_pk_fma_f32 v[86:87], v[102:103], v[134:135], v[86:87]
	v_lshlrev_b32_e32 v136, 16, v75
	v_and_b32_e32 v137, s7, v75
	v_pk_fma_f32 v[192:193], v[104:105], v[136:137], v[192:193]
	v_lshlrev_b32_e32 v138, 16, v76
	v_and_b32_e32 v139, s7, v76
	v_pk_fma_f32 v[194:195], v[106:107], v[138:139], v[194:195]
	v_lshlrev_b32_e32 v140, 16, v77
	v_and_b32_e32 v141, s7, v77
	v_pk_fma_f32 v[204:205], v[108:109], v[140:141], v[204:205]
	s_waitcnt lgkmcnt(15)
	v_lshlrev_b32_e32 v126, 16, v78
	v_and_b32_e32 v127, s7, v78
	v_pk_fma_f32 v[86:87], v[110:111], v[126:127], v[86:87]
	v_lshlrev_b32_e32 v128, 16, v79
	v_and_b32_e32 v129, s7, v79
	v_pk_fma_f32 v[192:193], v[112:113], v[128:129], v[192:193]
	v_lshlrev_b32_e32 v130, 16, v80
	v_and_b32_e32 v131, s7, v80
	v_pk_fma_f32 v[194:195], v[114:115], v[130:131], v[194:195]
	v_lshlrev_b32_e32 v132, 16, v81
	v_and_b32_e32 v133, s7, v81
	v_pk_fma_f32 v[204:205], v[116:117], v[132:133], v[204:205]
	s_waitcnt lgkmcnt(12)
	v_lshlrev_b32_e32 v134, 16, v82
	v_and_b32_e32 v135, s7, v82
	v_pk_fma_f32 v[86:87], v[118:119], v[134:135], v[86:87]
	v_lshlrev_b32_e32 v136, 16, v83
	v_and_b32_e32 v137, s7, v83
	v_pk_fma_f32 v[192:193], v[120:121], v[136:137], v[192:193]
	v_lshlrev_b32_e32 v138, 16, v84
	v_and_b32_e32 v139, s7, v84
	v_pk_fma_f32 v[194:195], v[122:123], v[138:139], v[194:195]
	v_lshlrev_b32_e32 v140, 16, v85
	v_and_b32_e32 v141, s7, v85
	v_pk_fma_f32 v[204:205], v[124:125], v[140:141], v[204:205]
	ds_read_b128 v[70:73], v68 offset:384
	ds_read_b128 v[94:97], v69 offset:768
	ds_read_b128 v[98:101], v69 offset:784
	ds_read_b128 v[74:77], v68 offset:400
	ds_read_b128 v[102:105], v69 offset:800
	ds_read_b128 v[106:109], v69 offset:816
	ds_read_b128 v[78:81], v68 offset:416
	ds_read_b128 v[110:113], v69 offset:832
	ds_read_b128 v[114:117], v69 offset:848
	ds_read_b128 v[82:85], v68 offset:432
	ds_read_b128 v[118:121], v69 offset:864
	ds_read_b128 v[122:125], v69 offset:880
	s_waitcnt lgkmcnt(15)
	v_lshlrev_b32_e32 v126, 16, v142
	v_and_b32_e32 v127, s7, v142
	v_pk_fma_f32 v[86:87], v[160:161], v[126:127], v[86:87]
	v_lshlrev_b32_e32 v128, 16, v143
	v_and_b32_e32 v129, s7, v143
	v_pk_fma_f32 v[192:193], v[162:163], v[128:129], v[192:193]
	v_lshlrev_b32_e32 v130, 16, v144
	v_and_b32_e32 v131, s7, v144
	v_pk_fma_f32 v[194:195], v[164:165], v[130:131], v[194:195]
	v_lshlrev_b32_e32 v132, 16, v145
	v_and_b32_e32 v133, s7, v145
	v_pk_fma_f32 v[204:205], v[166:167], v[132:133], v[204:205]
	s_waitcnt lgkmcnt(15)
	v_lshlrev_b32_e32 v134, 16, v146
	v_and_b32_e32 v135, s7, v146
	v_pk_fma_f32 v[86:87], v[168:169], v[134:135], v[86:87]
	v_lshlrev_b32_e32 v136, 16, v147
	v_and_b32_e32 v137, s7, v147
	v_pk_fma_f32 v[192:193], v[170:171], v[136:137], v[192:193]
	v_lshlrev_b32_e32 v138, 16, v148
	v_and_b32_e32 v139, s7, v148
	v_pk_fma_f32 v[194:195], v[172:173], v[138:139], v[194:195]
	v_lshlrev_b32_e32 v140, 16, v149
	v_and_b32_e32 v141, s7, v149
	v_pk_fma_f32 v[204:205], v[174:175], v[140:141], v[204:205]
	s_waitcnt lgkmcnt(15)
; #define LAS __attribute__((address_space(3)))
; __device__ __forceinline__ float bf_lo(unsigned w) { return __uint_as_float(w << 16); }
; __device__ __forceinline__ float bf_hi(unsigned w) { return __uint_as_float(w & 0xffff0000u); }
; __device__ void passB_unit(const Params& p, LAS unsigned char* lds, int u, bool do_store = true) {
;     ...
; #pragma unroll 4
;         for (int k8 = 0; k8 < 32; ++k8) { const u32x4 qv = *(const LAS u32x4*)(Qs + t * 264 + k8 * 8); const LAS float* np = nv + k8 * 8;
;             s += bf_lo(qv.x) * np[0] + bf_hi(qv.x) * np[1] + bf_lo(qv.y) * np[2] + bf_hi(qv.y) * np[3] + bf_lo(qv.z) * np[4] + bf_hi(qv.z) * np[5] + bf_lo(qv.w) * np[6] + bf_hi(qv.w) * np[7]; }
;         nqA[dt] = s; }
	v_lshlrev_b32_e32 v126, 16, v150
	v_and_b32_e32 v127, s7, v150
	v_pk_fma_f32 v[86:87], v[176:177], v[126:127], v[86:87]
	v_lshlrev_b32_e32 v128, 16, v151
	v_and_b32_e32 v129, s7, v151
	v_pk_fma_f32 v[192:193], v[178:179], v[128:129], v[192:193]
	v_lshlrev_b32_e32 v130, 16, v152
	v_and_b32_e32 v131, s7, v152
	v_pk_fma_f32 v[194:195], v[180:181], v[130:131], v[194:195]
	v_lshlrev_b32_e32 v132, 16, v153
	v_and_b32_e32 v133, s7, v153
	v_pk_fma_f32 v[204:205], v[182:183], v[132:133], v[204:205]
	s_waitcnt lgkmcnt(12)
	v_lshlrev_b32_e32 v134, 16, v154
	v_and_b32_e32 v135, s7, v154
	v_pk_fma_f32 v[86:87], v[184:185], v[134:135], v[86:87]
	v_lshlrev_b32_e32 v136, 16, v155
	v_and_b32_e32 v137, s7, v155
	v_pk_fma_f32 v[192:193], v[186:187], v[136:137], v[192:193]
	v_lshlrev_b32_e32 v138, 16, v156
	v_and_b32_e32 v139, s7, v156
	v_pk_fma_f32 v[194:195], v[188:189], v[138:139], v[194:195]
	v_lshlrev_b32_e32 v140, 16, v157
	v_and_b32_e32 v141, s7, v157
	v_pk_fma_f32 v[204:205], v[190:191], v[140:141], v[204:205]
	ds_read_b128 v[142:145], v68 offset:448
	ds_read_b128 v[160:163], v69 offset:896
	ds_read_b128 v[164:167], v69 offset:912
	ds_read_b128 v[146:149], v68 offset:464
	ds_read_b128 v[168:171], v69 offset:928
	ds_read_b128 v[172:175], v69 offset:944
	ds_read_b128 v[150:153], v68 offset:480
	ds_read_b128 v[176:179], v69 offset:960
	ds_read_b128 v[180:183], v69 offset:976
	ds_read_b128 v[154:157], v68 offset:496
	ds_read_b128 v[184:187], v69 offset:992
	ds_read_b128 v[188:191], v69 offset:1008
	s_waitcnt lgkmcnt(15)
	v_lshlrev_b32_e32 v126, 16, v70
	v_and_b32_e32 v127, s7, v70
	v_pk_fma_f32 v[86:87], v[94:95], v[126:127], v[86:87]
	v_lshlrev_b32_e32 v128, 16, v71
	v_and_b32_e32 v129, s7, v71
	v_pk_fma_f32 v[192:193], v[96:97], v[128:129], v[192:193]
	v_lshlrev_b32_e32 v130, 16, v72
	v_and_b32_e32 v131, s7, v72
	v_pk_fma_f32 v[194:195], v[98:99], v[130:131], v[194:195]
	v_lshlrev_b32_e32 v132, 16, v73
	v_and_b32_e32 v133, s7, v73
	v_pk_fma_f32 v[204:205], v[100:101], v[132:133], v[204:205]
	s_waitcnt lgkmcnt(15)
	v_lshlrev_b32_e32 v134, 16, v74
	v_and_b32_e32 v135, s7, v74
	v_pk_fma_f32 v[86:87], v[102:103], v[134:135], v[86:87]
	v_lshlrev_b32_e32 v136, 16, v75
	v_and_b32_e32 v137, s7, v75
	v_pk_fma_f32 v[192:193], v[104:105], v[136:137], v[192:193]
	v_lshlrev_b32_e32 v138, 16, v76
	v_and_b32_e32 v139, s7, v76
	v_pk_fma_f32 v[194:195], v[106:107], v[138:139], v[194:195]
	v_lshlrev_b32_e32 v140, 16, v77
	v_and_b32_e32 v141, s7, v77
	v_pk_fma_f32 v[204:205], v[108:109], v[140:141], v[204:205]
	s_waitcnt lgkmcnt(15)
	v_lshlrev_b32_e32 v126, 16, v78
	v_and_b32_e32 v127, s7, v78
	v_pk_fma_f32 v[86:87], v[110:111], v[126:127], v[86:87]
	v_lshlrev_b32_e32 v128, 16, v79
	v_and_b32_e32 v129, s7, v79
	v_pk_fma_f32 v[192:193], v[112:113], v[128:129], v[192:193]
	v_lshlrev_b32_e32 v130, 16, v80
	v_and_b32_e32 v131, s7, v80
	v_pk_fma_f32 v[194:195], v[114:115], v[130:131], v[194:195]
	v_lshlrev_b32_e32 v132, 16, v81
	v_and_b32_e32 v133, s7, v81
	v_pk_fma_f32 v[204:205], v[116:117], v[132:133], v[204:205]
	s_waitcnt lgkmcnt(12)
	v_lshlrev_b32_e32 v134, 16, v82
	v_and_b32_e32 v135, s7, v82
	v_pk_fma_f32 v[86:87], v[118:119], v[134:135], v[86:87]
	v_lshlrev_b32_e32 v136, 16, v83
	v_and_b32_e32 v137, s7, v83
	v_pk_fma_f32 v[192:193], v[120:121], v[136:137], v[192:193]
	v_lshlrev_b32_e32 v138, 16, v84
	v_and_b32_e32 v139, s7, v84
	v_pk_fma_f32 v[194:195], v[122:123], v[138:139], v[194:195]
	v_lshlrev_b32_e32 v140, 16, v85
	v_and_b32_e32 v141, s7, v85
	v_pk_fma_f32 v[204:205], v[124:125], v[140:141], v[204:205]
	s_waitcnt lgkmcnt(9)
	v_lshlrev_b32_e32 v126, 16, v142
	v_and_b32_e32 v127, s7, v142
	v_pk_fma_f32 v[86:87], v[160:161], v[126:127], v[86:87]
	v_lshlrev_b32_e32 v128, 16, v143
	v_and_b32_e32 v129, s7, v143
	v_pk_fma_f32 v[192:193], v[162:163], v[128:129], v[192:193]
	v_lshlrev_b32_e32 v130, 16, v144
	v_and_b32_e32 v131, s7, v144
	v_pk_fma_f32 v[194:195], v[164:165], v[130:131], v[194:195]
	v_lshlrev_b32_e32 v132, 16, v145
	v_and_b32_e32 v133, s7, v145
	v_pk_fma_f32 v[204:205], v[166:167], v[132:133], v[204:205]
	s_waitcnt lgkmcnt(6)
	v_lshlrev_b32_e32 v134, 16, v146
	v_and_b32_e32 v135, s7, v146
	v_pk_fma_f32 v[86:87], v[168:169], v[134:135], v[86:87]
	v_lshlrev_b32_e32 v136, 16, v147
	v_and_b32_e32 v137, s7, v147
	v_pk_fma_f32 v[192:193], v[170:171], v[136:137], v[192:193]
	v_lshlrev_b32_e32 v138, 16, v148
	v_and_b32_e32 v139, s7, v148
	v_pk_fma_f32 v[194:195], v[172:173], v[138:139], v[194:195]
	v_lshlrev_b32_e32 v140, 16, v149
	v_and_b32_e32 v141, s7, v149
	v_pk_fma_f32 v[204:205], v[174:175], v[140:141], v[204:205]
	s_waitcnt lgkmcnt(3)
	v_lshlrev_b32_e32 v126, 16, v150
	v_and_b32_e32 v127, s7, v150
	v_pk_fma_f32 v[86:87], v[176:177], v[126:127], v[86:87]
	v_lshlrev_b32_e32 v128, 16, v151
	v_and_b32_e32 v129, s7, v151
	v_pk_fma_f32 v[192:193], v[178:179], v[128:129], v[192:193]
	v_lshlrev_b32_e32 v130, 16, v152
	v_and_b32_e32 v131, s7, v152
	v_pk_fma_f32 v[194:195], v[180:181], v[130:131], v[194:195]
	v_lshlrev_b32_e32 v132, 16, v153
	v_and_b32_e32 v133, s7, v153
	v_pk_fma_f32 v[204:205], v[182:183], v[132:133], v[204:205]
	s_waitcnt lgkmcnt(0)
	v_lshlrev_b32_e32 v134, 16, v154
	v_and_b32_e32 v135, s7, v154
	v_pk_fma_f32 v[86:87], v[184:185], v[134:135], v[86:87]
	v_lshlrev_b32_e32 v136, 16, v155
	v_and_b32_e32 v137, s7, v155
	v_pk_fma_f32 v[192:193], v[186:187], v[136:137], v[192:193]
	v_lshlrev_b32_e32 v138, 16, v156
	v_and_b32_e32 v139, s7, v156
	v_pk_fma_f32 v[194:195], v[188:189], v[138:139], v[194:195]
	v_lshlrev_b32_e32 v140, 16, v157
	v_and_b32_e32 v141, s7, v157
	v_pk_fma_f32 v[204:205], v[190:191], v[140:141], v[204:205]
	v_pk_add_f32 v[86:87], v[86:87], v[192:193]
	v_pk_add_f32 v[194:195], v[194:195], v[204:205]
	v_pk_add_f32 v[86:87], v[86:87], v[194:195]
	v_add_f32_e32 v60, v86, v87
	v_add_u32_e32 v61, 0x23000, v63
	ds_write_b32 v61, v60

; #define LAS __attribute__((address_space(3)))
; __device__ __forceinline__ float bf_lo(unsigned w) { return __uint_as_float(w << 16); }
; __device__ __forceinline__ float bf_hi(unsigned w) { return __uint_as_float(w & 0xffff0000u); }
; __device__ void passB_unit(const Params& p, LAS unsigned char* lds, int u, bool do_store = true) {
;     ...
;     if (tid < 256) { const int d = tid >> 7, t = sc_t; if (wid & 1) sc_pm = fmaxf(sc_pm, wmax[wid - 1]);
;         const float mc = ((const float*)(p.ws + OFF_MST))[(sid0 + d) * 16 + c];
;         const float Mt = fmaxf(mc, sc_pm); const int dt = d * 128 + t;
;         aA[dt] = sc_a; MA[dt] = Mt; winA[dt] = expf(mc - Mt); clampA[dt] = expf(-(sc_b + Mt));
;         float s = 0.f; const LAS float* nv = nvec + d * 256;
; #pragma unroll 4
;         for (int k8 = 0; k8 < 32; ++k8) { const u32x4 qv = *(const LAS u32x4*)(Qs + t * 264 + k8 * 8); const LAS float* np = nv + k8 * 8;
;             s += bf_lo(qv.x) * np[0] + bf_hi(qv.x) * np[1] + bf_lo(qv.y) * np[2] + bf_hi(qv.y) * np[3] + bf_lo(qv.z) * np[4] + bf_hi(qv.z) * np[5] + bf_lo(qv.w) * np[6] + bf_hi(qv.w) * np[7]; }
;         nqA[dt] = s; }
.LBB0_582:
	s_or_b64 exec, exec, s[6:7]
	v_ashrrev_i32_e32 v71, 7, v196
	v_add_u32_e32 v60, s50, v71
	v_lshl_or_b32 v72, v60, 4, s24
	v_ashrrev_i32_e32 v73, 31, v72
	v_lshl_add_u64 v[72:73], v[72:73], 2, s[14:15]
	global_load_dword v72, v[72:73], off
	v_max_f32_e32 v70, v70, v70
	s_mov_b32 s10, 0x3fb8aa3b
	s_mov_b32 s15, 0xbfb8aa3b
	s_movk_i32 s7, 0xff80
	s_movk_i32 s28, 0x210
	v_and_or_b32 v74, v196, s7, v63
	v_mad_i32_i24 v68, v63, s28, 0
	v_lshl_add_u32 v63, v74, 2, 0
	s_mov_b32 s11, 0xc2ce8ed0
	v_add_u32_e32 v74, 0x22000, v63
	s_mov_b32 s25, 0x42ce8ed0
	v_add_u32_e32 v75, 0x22400, v63
	s_mov_b32 s14, 0x42b17218
	v_mov_b32_e32 v73, 0x7f800000
	s_mov_b32 s26, 0xc2b17218
	v_add_u32_e32 v76, 0x22800, v63
	s_mov_b32 s6, 0
	v_mov_b32_e32 v60, 0
	v_add_u32_e32 v77, 0x22c00, v63
	s_waitcnt vmcnt(0)
	v_max_f32_e32 v78, v72, v72
	v_max_f32_e32 v70, v78, v70
	v_sub_f32_e32 v72, v72, v70
	v_add_f32_e32 v69, v69, v70
	v_mul_f32_e32 v78, 0x3fb8aa3b, v72
	v_mul_f32_e32 v79, 0xbfb8aa3b, v69
	v_fma_f32 v80, v72, s10, -v78
	v_rndne_f32_e32 v81, v78
	v_fma_f32 v82, v69, s15, -v79
	v_rndne_f32_e32 v83, v79
	v_fmamk_f32 v80, v72, 0x32a5705f, v80
	v_sub_f32_e32 v78, v78, v81
	v_fmamk_f32 v82, v69, 0xb2a5705f, v82
	v_sub_f32_e32 v79, v79, v83
	v_add_f32_e32 v78, v78, v80
	v_cvt_i32_f32_e32 v81, v81
	v_add_f32_e32 v79, v79, v82
	v_exp_f32_e32 v78, v78
	v_cvt_i32_f32_e32 v83, v83
	v_exp_f32_e32 v79, v79
	ds_write_b32 v74, v61
	ds_write_b32 v75, v70
	v_ldexp_f32 v61, v78, v81
	v_cmp_ngt_f32_e32 vcc, s11, v72
	v_ldexp_f32 v70, v79, v83
	s_nop 0
	v_cndmask_b32_e32 v61, 0, v61, vcc
	v_cmp_nlt_f32_e32 vcc, s25, v69
	s_nop 1
	v_cndmask_b32_e32 v70, 0, v70, vcc
	v_cmp_nlt_f32_e32 vcc, s14, v72
	s_nop 1
	v_cndmask_b32_e32 v61, v73, v61, vcc
	v_cmp_ngt_f32_e32 vcc, s26, v69
	s_nop 1
	v_cndmask_b32_e32 v69, v73, v70, vcc
	ds_write_b32 v76, v61
	ds_write_b32 v77, v69
	v_lshl_add_u32 v61, v71, 10, 0
	v_add_u32_e32 v69, 0x23400, v61
	s_mov_b32 s7, 0xffff0000
	ds_read_b128 v[70:73], v68 offset:0
	ds_read_b128 v[94:97], v69 offset:0
	ds_read_b128 v[98:101], v69 offset:16
	ds_read_b128 v[74:77], v68 offset:16
	ds_read_b128 v[102:105], v69 offset:32
	ds_read_b128 v[106:109], v69 offset:48
	ds_read_b128 v[78:81], v68 offset:32
	ds_read_b128 v[110:113], v69 offset:64
	ds_read_b128 v[114:117], v69 offset:80
	ds_read_b128 v[82:85], v68 offset:48
	ds_read_b128 v[118:121], v69 offset:96
	ds_read_b128 v[122:125], v69 offset:112
	ds_read_b128 v[142:145], v68 offset:64
	ds_read_b128 v[160:163], v69 offset:128
	ds_read_b128 v[164:167], v69 offset:144
	ds_read_b128 v[146:149], v68 offset:80
	ds_read_b128 v[168:171], v69 offset:160
	ds_read_b128 v[172:175], v69 offset:176
	ds_read_b128 v[150:153], v68 offset:96
	ds_read_b128 v[176:179], v69 offset:192
	ds_read_b128 v[180:183], v69 offset:208
	ds_read_b128 v[154:157], v68 offset:112
	ds_read_b128 v[184:187], v69 offset:224
	ds_read_b128 v[188:191], v69 offset:240
	s_waitcnt lgkmcnt(15)
	v_lshlrev_b32_e32 v126, 16, v70
	v_and_b32_e32 v127, s7, v70
	v_pk_mul_f32 v[86:87], v[94:95], v[126:127]
	v_lshlrev_b32_e32 v128, 16, v71
	v_and_b32_e32 v129, s7, v71
	v_pk_mul_f32 v[192:193], v[96:97], v[128:129]
	v_lshlrev_b32_e32 v130, 16, v72
	v_and_b32_e32 v131, s7, v72
	v_pk_mul_f32 v[194:195], v[98:99], v[130:131]
	v_lshlrev_b32_e32 v132, 16, v73
	v_and_b32_e32 v133, s7, v73
	v_pk_mul_f32 v[204:205], v[100:101], v[132:133]
	s_waitcnt lgkmcnt(15)
	v_lshlrev_b32_e32 v134, 16, v74
	v_and_b32_e32 v135, s7, v74
	v_pk_fma_f32 v[86:87], v[102:103], v[134:135], v[86:87]
	v_lshlrev_b32_e32 v136, 16, v75
	v_and_b32_e32 v137, s7, v75
	v_pk_fma_f32 v[192:193], v[104:105], v[136:137], v[192:193]
	v_lshlrev_b32_e32 v138, 16, v76
	v_and_b32_e32 v139, s7, v76
	v_pk_fma_f32 v[194:195], v[106:107], v[138:139], v[194:195]
	v_lshlrev_b32_e32 v140, 16, v77
	v_and_b32_e32 v141, s7, v77
	v_pk_fma_f32 v[204:205], v[108:109], v[140:141], v[204:205]
	s_waitcnt lgkmcnt(15)
	v_lshlrev_b32_e32 v126, 16, v78
	v_and_b32_e32 v127, s7, v78
	v_pk_fma_f32 v[86:87], v[110:111], v[126:127], v[86:87]
	v_lshlrev_b32_e32 v128, 16, v79
	v_and_b32_e32 v129, s7, v79
	v_pk_fma_f32 v[192:193], v[112:113], v[128:129], v[192:193]
	v_lshlrev_b32_e32 v130, 16, v80
	v_and_b32_e32 v131, s7, v80
	v_pk_fma_f32 v[194:195], v[114:115], v[130:131], v[194:195]
	v_lshlrev_b32_e32 v132, 16, v81
	v_and_b32_e32 v133, s7, v81
	v_pk_fma_f32 v[204:205], v[116:117], v[132:133], v[204:205]
	s_waitcnt lgkmcnt(12)
	v_lshlrev_b32_e32 v134, 16, v82
	v_and_b32_e32 v135, s7, v82
	v_pk_fma_f32 v[86:87], v[118:119], v[134:135], v[86:87]
	v_lshlrev_b32_e32 v136, 16, v83
	v_and_b32_e32 v137, s7, v83
	v_pk_fma_f32 v[192:193], v[120:121], v[136:137], v[192:193]
	v_lshlrev_b32_e32 v138, 16, v84
	v_and_b32_e32 v139, s7, v84
	v_pk_fma_f32 v[194:195], v[122:123], v[138:139], v[194:195]
	v_lshlrev_b32_e32 v140, 16, v85
	v_and_b32_e32 v141, s7, v85
	v_pk_fma_f32 v[204:205], v[124:125], v[140:141], v[204:205]
	ds_read_b128 v[70:73], v68 offset:128
	ds_read_b128 v[94:97], v69 offset:256
	ds_read_b128 v[98:101], v69 offset:272
	ds_read_b128 v[74:77], v68 offset:144
	ds_read_b128 v[102:105], v69 offset:288
	ds_read_b128 v[106:109], v69 offset:304
	ds_read_b128 v[78:81], v68 offset:160
	ds_read_b128 v[110:113], v69 offset:320
	ds_read_b128 v[114:117], v69 offset:336
	ds_read_b128 v[82:85], v68 offset:176
	ds_read_b128 v[118:121], v69 offset:352
	ds_read_b128 v[122:125], v69 offset:368
	s_waitcnt lgkmcnt(15)
; #define LAS __attribute__((address_space(3)))
; __device__ __forceinline__ float bf_lo(unsigned w) { return __uint_as_float(w << 16); }
; __device__ __forceinline__ float bf_hi(unsigned w) { return __uint_as_float(w & 0xffff0000u); }
; __device__ void passB_unit(const Params& p, LAS unsigned char* lds, int u, bool do_store = true) {
;     ...
;         for (int k8 = 0; k8 < 32; ++k8) { const u32x4 qv = *(const LAS u32x4*)(Qs + t * 264 + k8 * 8); const LAS float* np = nv + k8 * 8;
;             s += bf_lo(qv.x) * np[0] + bf_hi(qv.x) * np[1] + bf_lo(qv.y) * np[2] + bf_hi(qv.y) * np[3] + bf_lo(qv.z) * np[4] + bf_hi(qv.z) * np[5] + bf_lo(qv.w) * np[6] + bf_hi(qv.w) * np[7]; }
	v_lshlrev_b32_e32 v126, 16, v142
	v_and_b32_e32 v127, s7, v142
	v_pk_fma_f32 v[86:87], v[160:161], v[126:127], v[86:87]
	v_lshlrev_b32_e32 v128, 16, v143
	v_and_b32_e32 v129, s7, v143
	v_pk_fma_f32 v[192:193], v[162:163], v[128:129], v[192:193]
	v_lshlrev_b32_e32 v130, 16, v144
	v_and_b32_e32 v131, s7, v144
	v_pk_fma_f32 v[194:195], v[164:165], v[130:131], v[194:195]
	v_lshlrev_b32_e32 v132, 16, v145
	v_and_b32_e32 v133, s7, v145
	v_pk_fma_f32 v[204:205], v[166:167], v[132:133], v[204:205]
	s_waitcnt lgkmcnt(15)
	v_lshlrev_b32_e32 v134, 16, v146
	v_and_b32_e32 v135, s7, v146
	v_pk_fma_f32 v[86:87], v[168:169], v[134:135], v[86:87]
	v_lshlrev_b32_e32 v136, 16, v147
	v_and_b32_e32 v137, s7, v147
	v_pk_fma_f32 v[192:193], v[170:171], v[136:137], v[192:193]
	v_lshlrev_b32_e32 v138, 16, v148
	v_and_b32_e32 v139, s7, v148
	v_pk_fma_f32 v[194:195], v[172:173], v[138:139], v[194:195]
	v_lshlrev_b32_e32 v140, 16, v149
	v_and_b32_e32 v141, s7, v149
	v_pk_fma_f32 v[204:205], v[174:175], v[140:141], v[204:205]
	s_waitcnt lgkmcnt(15)
	v_lshlrev_b32_e32 v126, 16, v150
	v_and_b32_e32 v127, s7, v150
	v_pk_fma_f32 v[86:87], v[176:177], v[126:127], v[86:87]
	v_lshlrev_b32_e32 v128, 16, v151
	v_and_b32_e32 v129, s7, v151
	v_pk_fma_f32 v[192:193], v[178:179], v[128:129], v[192:193]
	v_lshlrev_b32_e32 v130, 16, v152
	v_and_b32_e32 v131, s7, v152
	v_pk_fma_f32 v[194:195], v[180:181], v[130:131], v[194:195]
	v_lshlrev_b32_e32 v132, 16, v153
	v_and_b32_e32 v133, s7, v153
	v_pk_fma_f32 v[204:205], v[182:183], v[132:133], v[204:205]
	s_waitcnt lgkmcnt(12)
	v_lshlrev_b32_e32 v134, 16, v154
	v_and_b32_e32 v135, s7, v154
	v_pk_fma_f32 v[86:87], v[184:185], v[134:135], v[86:87]
	v_lshlrev_b32_e32 v136, 16, v155
	v_and_b32_e32 v137, s7, v155
	v_pk_fma_f32 v[192:193], v[186:187], v[136:137], v[192:193]
	v_lshlrev_b32_e32 v138, 16, v156
	v_and_b32_e32 v139, s7, v156
	v_pk_fma_f32 v[194:195], v[188:189], v[138:139], v[194:195]
	v_lshlrev_b32_e32 v140, 16, v157
	v_and_b32_e32 v141, s7, v157
	v_pk_fma_f32 v[204:205], v[190:191], v[140:141], v[204:205]
	ds_read_b128 v[142:145], v68 offset:192
	ds_read_b128 v[160:163], v69 offset:384
	ds_read_b128 v[164:167], v69 offset:400
	ds_read_b128 v[146:149], v68 offset:208
	ds_read_b128 v[168:171], v69 offset:416
	ds_read_b128 v[172:175], v69 offset:432
	ds_read_b128 v[150:153], v68 offset:224
	ds_read_b128 v[176:179], v69 offset:448
	ds_read_b128 v[180:183], v69 offset:464
	ds_read_b128 v[154:157], v68 offset:240
	ds_read_b128 v[184:187], v69 offset:480
	ds_read_b128 v[188:191], v69 offset:496
	s_waitcnt lgkmcnt(15)
	v_lshlrev_b32_e32 v126, 16, v70
	v_and_b32_e32 v127, s7, v70
	v_pk_fma_f32 v[86:87], v[94:95], v[126:127], v[86:87]
	v_lshlrev_b32_e32 v128, 16, v71
	v_and_b32_e32 v129, s7, v71
	v_pk_fma_f32 v[192:193], v[96:97], v[128:129], v[192:193]
	v_lshlrev_b32_e32 v130, 16, v72
	v_and_b32_e32 v131, s7, v72
	v_pk_fma_f32 v[194:195], v[98:99], v[130:131], v[194:195]
	v_lshlrev_b32_e32 v132, 16, v73
	v_and_b32_e32 v133, s7, v73
	v_pk_fma_f32 v[204:205], v[100:101], v[132:133], v[204:205]
	s_waitcnt lgkmcnt(15)
	v_lshlrev_b32_e32 v134, 16, v74
	v_and_b32_e32 v135, s7, v74
	v_pk_fma_f32 v[86:87], v[102:103], v[134:135], v[86:87]
	v_lshlrev_b32_e32 v136, 16, v75
	v_and_b32_e32 v137, s7, v75
	v_pk_fma_f32 v[192:193], v[104:105], v[136:137], v[192:193]
	v_lshlrev_b32_e32 v138, 16, v76
	v_and_b32_e32 v139, s7, v76
	v_pk_fma_f32 v[194:195], v[106:107], v[138:139], v[194:195]
	v_lshlrev_b32_e32 v140, 16, v77
	v_and_b32_e32 v141, s7, v77
	v_pk_fma_f32 v[204:205], v[108:109], v[140:141], v[204:205]
	s_waitcnt lgkmcnt(15)
	v_lshlrev_b32_e32 v126, 16, v78
	v_and_b32_e32 v127, s7, v78
	v_pk_fma_f32 v[86:87], v[110:111], v[126:127], v[86:87]
	v_lshlrev_b32_e32 v128, 16, v79
	v_and_b32_e32 v129, s7, v79
	v_pk_fma_f32 v[192:193], v[112:113], v[128:129], v[192:193]
	v_lshlrev_b32_e32 v130, 16, v80
	v_and_b32_e32 v131, s7, v80
	v_pk_fma_f32 v[194:195], v[114:115], v[130:131], v[194:195]
	v_lshlrev_b32_e32 v132, 16, v81
	v_and_b32_e32 v133, s7, v81
	v_pk_fma_f32 v[204:205], v[116:117], v[132:133], v[204:205]
	s_waitcnt lgkmcnt(12)
	v_lshlrev_b32_e32 v134, 16, v82
	v_and_b32_e32 v135, s7, v82
	v_pk_fma_f32 v[86:87], v[118:119], v[134:135], v[86:87]
	v_lshlrev_b32_e32 v136, 16, v83
	v_and_b32_e32 v137, s7, v83
	v_pk_fma_f32 v[192:193], v[120:121], v[136:137], v[192:193]
	v_lshlrev_b32_e32 v138, 16, v84
	v_and_b32_e32 v139, s7, v84
	v_pk_fma_f32 v[194:195], v[122:123], v[138:139], v[194:195]
	v_lshlrev_b32_e32 v140, 16, v85
	v_and_b32_e32 v141, s7, v85
	v_pk_fma_f32 v[204:205], v[124:125], v[140:141], v[204:205]
	ds_read_b128 v[70:73], v68 offset:256
	ds_read_b128 v[94:97], v69 offset:512
	ds_read_b128 v[98:101], v69 offset:528
	ds_read_b128 v[74:77], v68 offset:272
	ds_read_b128 v[102:105], v69 offset:544
	ds_read_b128 v[106:109], v69 offset:560
	ds_read_b128 v[78:81], v68 offset:288
	ds_read_b128 v[110:113], v69 offset:576
	ds_read_b128 v[114:117], v69 offset:592
	ds_read_b128 v[82:85], v68 offset:304
	ds_read_b128 v[118:121], v69 offset:608
	ds_read_b128 v[122:125], v69 offset:624
	s_waitcnt lgkmcnt(15)
	v_lshlrev_b32_e32 v126, 16, v142
	v_and_b32_e32 v127, s7, v142
	v_pk_fma_f32 v[86:87], v[160:161], v[126:127], v[86:87]
	v_lshlrev_b32_e32 v128, 16, v143
	v_and_b32_e32 v129, s7, v143
	v_pk_fma_f32 v[192:193], v[162:163], v[128:129], v[192:193]
	v_lshlrev_b32_e32 v130, 16, v144
	v_and_b32_e32 v131, s7, v144
	v_pk_fma_f32 v[194:195], v[164:165], v[130:131], v[194:195]
	v_lshlrev_b32_e32 v132, 16, v145
	v_and_b32_e32 v133, s7, v145
	v_pk_fma_f32 v[204:205], v[166:167], v[132:133], v[204:205]
	s_waitcnt lgkmcnt(15)
; #define LAS __attribute__((address_space(3)))
; __device__ __forceinline__ float bf_lo(unsigned w) { return __uint_as_float(w << 16); }
; __device__ __forceinline__ float bf_hi(unsigned w) { return __uint_as_float(w & 0xffff0000u); }
; __device__ void passB_unit(const Params& p, LAS unsigned char* lds, int u, bool do_store = true) {
;     ...
;         for (int k8 = 0; k8 < 32; ++k8) { const u32x4 qv = *(const LAS u32x4*)(Qs + t * 264 + k8 * 8); const LAS float* np = nv + k8 * 8;
;             s += bf_lo(qv.x) * np[0] + bf_hi(qv.x) * np[1] + bf_lo(qv.y) * np[2] + bf_hi(qv.y) * np[3] + bf_lo(qv.z) * np[4] + bf_hi(qv.z) * np[5] + bf_lo(qv.w) * np[6] + bf_hi(qv.w) * np[7]; }
	v_lshlrev_b32_e32 v134, 16, v146
	v_and_b32_e32 v135, s7, v146
	v_pk_fma_f32 v[86:87], v[168:169], v[134:135], v[86:87]
	v_lshlrev_b32_e32 v136, 16, v147
	v_and_b32_e32 v137, s7, v147
	v_pk_fma_f32 v[192:193], v[170:171], v[136:137], v[192:193]
	v_lshlrev_b32_e32 v138, 16, v148
	v_and_b32_e32 v139, s7, v148
	v_pk_fma_f32 v[194:195], v[172:173], v[138:139], v[194:195]
	v_lshlrev_b32_e32 v140, 16, v149
	v_and_b32_e32 v141, s7, v149
	v_pk_fma_f32 v[204:205], v[174:175], v[140:141], v[204:205]
	s_waitcnt lgkmcnt(15)
	v_lshlrev_b32_e32 v126, 16, v150
	v_and_b32_e32 v127, s7, v150
	v_pk_fma_f32 v[86:87], v[176:177], v[126:127], v[86:87]
	v_lshlrev_b32_e32 v128, 16, v151
	v_and_b32_e32 v129, s7, v151
	v_pk_fma_f32 v[192:193], v[178:179], v[128:129], v[192:193]
	v_lshlrev_b32_e32 v130, 16, v152
	v_and_b32_e32 v131, s7, v152
	v_pk_fma_f32 v[194:195], v[180:181], v[130:131], v[194:195]
	v_lshlrev_b32_e32 v132, 16, v153
	v_and_b32_e32 v133, s7, v153
	v_pk_fma_f32 v[204:205], v[182:183], v[132:133], v[204:205]
	s_waitcnt lgkmcnt(12)
	v_lshlrev_b32_e32 v134, 16, v154
	v_and_b32_e32 v135, s7, v154
	v_pk_fma_f32 v[86:87], v[184:185], v[134:135], v[86:87]
	v_lshlrev_b32_e32 v136, 16, v155
	v_and_b32_e32 v137, s7, v155
	v_pk_fma_f32 v[192:193], v[186:187], v[136:137], v[192:193]
	v_lshlrev_b32_e32 v138, 16, v156
	v_and_b32_e32 v139, s7, v156
	v_pk_fma_f32 v[194:195], v[188:189], v[138:139], v[194:195]
	v_lshlrev_b32_e32 v140, 16, v157
	v_and_b32_e32 v141, s7, v157
	v_pk_fma_f32 v[204:205], v[190:191], v[140:141], v[204:205]
	ds_read_b128 v[142:145], v68 offset:320
	ds_read_b128 v[160:163], v69 offset:640
	ds_read_b128 v[164:167], v69 offset:656
	ds_read_b128 v[146:149], v68 offset:336
	ds_read_b128 v[168:171], v69 offset:672
	ds_read_b128 v[172:175], v69 offset:688
	ds_read_b128 v[150:153], v68 offset:352
	ds_read_b128 v[176:179], v69 offset:704
	ds_read_b128 v[180:183], v69 offset:720
	ds_read_b128 v[154:157], v68 offset:368
	ds_read_b128 v[184:187], v69 offset:736
	ds_read_b128 v[188:191], v69 offset:752
	s_waitcnt lgkmcnt(15)
	v_lshlrev_b32_e32 v126, 16, v70
	v_and_b32_e32 v127, s7, v70
	v_pk_fma_f32 v[86:87], v[94:95], v[126:127], v[86:87]
	v_lshlrev_b32_e32 v128, 16, v71
	v_and_b32_e32 v129, s7, v71
	v_pk_fma_f32 v[192:193], v[96:97], v[128:129], v[192:193]
	v_lshlrev_b32_e32 v130, 16, v72
	v_and_b32_e32 v131, s7, v72
	v_pk_fma_f32 v[194:195], v[98:99], v[130:131], v[194:195]
	v_lshlrev_b32_e32 v132, 16, v73
	v_and_b32_e32 v133, s7, v73
	v_pk_fma_f32 v[204:205], v[100:101], v[132:133], v[204:205]
	s_waitcnt lgkmcnt(15)
	v_lshlrev_b32_e32 v134, 16, v74
	v_and_b32_e32 v135, s7, v74
	v_pk_fma_f32 v[86:87], v[102:103], v[134:135], v[86:87]
	v_lshlrev_b32_e32 v136, 16, v75
	v_and_b32_e32 v137, s7, v75
	v_pk_fma_f32 v[192:193], v[104:105], v[136:137], v[192:193]
	v_lshlrev_b32_e32 v138, 16, v76
	v_and_b32_e32 v139, s7, v76
	v_pk_fma_f32 v[194:195], v[106:107], v[138:139], v[194:195]
	v_lshlrev_b32_e32 v140, 16, v77
	v_and_b32_e32 v141, s7, v77
	v_pk_fma_f32 v[204:205], v[108:109], v[140:141], v[204:205]
	s_waitcnt lgkmcnt(15)
	v_lshlrev_b32_e32 v126, 16, v78
	v_and_b32_e32 v127, s7, v78
	v_pk_fma_f32 v[86:87], v[110:111], v[126:127], v[86:87]
	v_lshlrev_b32_e32 v128, 16, v79
	v_and_b32_e32 v129, s7, v79
	v_pk_fma_f32 v[192:193], v[112:113], v[128:129], v[192:193]
	v_lshlrev_b32_e32 v130, 16, v80
	v_and_b32_e32 v131, s7, v80
	v_pk_fma_f32 v[194:195], v[114:115], v[130:131], v[194:195]
	v_lshlrev_b32_e32 v132, 16, v81
	v_and_b32_e32 v133, s7, v81
	v_pk_fma_f32 v[204:205], v[116:117], v[132:133], v[204:205]
	s_waitcnt lgkmcnt(12)
	v_lshlrev_b32_e32 v134, 16, v82
	v_and_b32_e32 v135, s7, v82
	v_pk_fma_f32 v[86:87], v[118:119], v[134:135], v[86:87]
	v_lshlrev_b32_e32 v136, 16, v83
	v_and_b32_e32 v137, s7, v83
	v_pk_fma_f32 v[192:193], v[120:121], v[136:137], v[192:193]
	v_lshlrev_b32_e32 v138, 16, v84
	v_and_b32_e32 v139, s7, v84
	v_pk_fma_f32 v[194:195], v[122:123], v[138:139], v[194:195]
	v_lshlrev_b32_e32 v140, 16, v85
	v_and_b32_e32 v141, s7, v85
	v_pk_fma_f32 v[204:205], v[124:125], v[140:141], v[204:205]
	ds_read_b128 v[70:73], v68 offset:384
	ds_read_b128 v[94:97], v69 offset:768
	ds_read_b128 v[98:101], v69 offset:784
	ds_read_b128 v[74:77], v68 offset:400
	ds_read_b128 v[102:105], v69 offset:800
	ds_read_b128 v[106:109], v69 offset:816
	ds_read_b128 v[78:81], v68 offset:416
	ds_read_b128 v[110:113], v69 offset:832
	ds_read_b128 v[114:117], v69 offset:848
	ds_read_b128 v[82:85], v68 offset:432
	ds_read_b128 v[118:121], v69 offset:864
	ds_read_b128 v[122:125], v69 offset:880
	s_waitcnt lgkmcnt(15)
	v_lshlrev_b32_e32 v126, 16, v142
	v_and_b32_e32 v127, s7, v142
	v_pk_fma_f32 v[86:87], v[160:161], v[126:127], v[86:87]
	v_lshlrev_b32_e32 v128, 16, v143
	v_and_b32_e32 v129, s7, v143
	v_pk_fma_f32 v[192:193], v[162:163], v[128:129], v[192:193]
	v_lshlrev_b32_e32 v130, 16, v144
	v_and_b32_e32 v131, s7, v144
	v_pk_fma_f32 v[194:195], v[164:165], v[130:131], v[194:195]
	v_lshlrev_b32_e32 v132, 16, v145
	v_and_b32_e32 v133, s7, v145
	v_pk_fma_f32 v[204:205], v[166:167], v[132:133], v[204:205]
	s_waitcnt lgkmcnt(15)
	v_lshlrev_b32_e32 v134, 16, v146
	v_and_b32_e32 v135, s7, v146
	v_pk_fma_f32 v[86:87], v[168:169], v[134:135], v[86:87]
	v_lshlrev_b32_e32 v136, 16, v147
	v_and_b32_e32 v137, s7, v147
	v_pk_fma_f32 v[192:193], v[170:171], v[136:137], v[192:193]
	v_lshlrev_b32_e32 v138, 16, v148
	v_and_b32_e32 v139, s7, v148
	v_pk_fma_f32 v[194:195], v[172:173], v[138:139], v[194:195]
	v_lshlrev_b32_e32 v140, 16, v149
	v_and_b32_e32 v141, s7, v149
	v_pk_fma_f32 v[204:205], v[174:175], v[140:141], v[204:205]
	s_waitcnt lgkmcnt(15)
; #define LAS __attribute__((address_space(3)))
; __device__ __forceinline__ float bf_lo(unsigned w) { return __uint_as_float(w << 16); }
; __device__ __forceinline__ float bf_hi(unsigned w) { return __uint_as_float(w & 0xffff0000u); }
; __device__ void passB_unit(const Params& p, LAS unsigned char* lds, int u, bool do_store = true) {
;     ...
; #pragma unroll 4
;         for (int k8 = 0; k8 < 32; ++k8) { const u32x4 qv = *(const LAS u32x4*)(Qs + t * 264 + k8 * 8); const LAS float* np = nv + k8 * 8;
;             s += bf_lo(qv.x) * np[0] + bf_hi(qv.x) * np[1] + bf_lo(qv.y) * np[2] + bf_hi(qv.y) * np[3] + bf_lo(qv.z) * np[4] + bf_hi(qv.z) * np[5] + bf_lo(qv.w) * np[6] + bf_hi(qv.w) * np[7]; }
;         nqA[dt] = s; }
	v_lshlrev_b32_e32 v126, 16, v150
	v_and_b32_e32 v127, s7, v150
	v_pk_fma_f32 v[86:87], v[176:177], v[126:127], v[86:87]
	v_lshlrev_b32_e32 v128, 16, v151
	v_and_b32_e32 v129, s7, v151
	v_pk_fma_f32 v[192:193], v[178:179], v[128:129], v[192:193]
	v_lshlrev_b32_e32 v130, 16, v152
	v_and_b32_e32 v131, s7, v152
	v_pk_fma_f32 v[194:195], v[180:181], v[130:131], v[194:195]
	v_lshlrev_b32_e32 v132, 16, v153
	v_and_b32_e32 v133, s7, v153
	v_pk_fma_f32 v[204:205], v[182:183], v[132:133], v[204:205]
	s_waitcnt lgkmcnt(12)
	v_lshlrev_b32_e32 v134, 16, v154
	v_and_b32_e32 v135, s7, v154
	v_pk_fma_f32 v[86:87], v[184:185], v[134:135], v[86:87]
	v_lshlrev_b32_e32 v136, 16, v155
	v_and_b32_e32 v137, s7, v155
	v_pk_fma_f32 v[192:193], v[186:187], v[136:137], v[192:193]
	v_lshlrev_b32_e32 v138, 16, v156
	v_and_b32_e32 v139, s7, v156
	v_pk_fma_f32 v[194:195], v[188:189], v[138:139], v[194:195]
	v_lshlrev_b32_e32 v140, 16, v157
	v_and_b32_e32 v141, s7, v157
	v_pk_fma_f32 v[204:205], v[190:191], v[140:141], v[204:205]
	ds_read_b128 v[142:145], v68 offset:448
	ds_read_b128 v[160:163], v69 offset:896
	ds_read_b128 v[164:167], v69 offset:912
	ds_read_b128 v[146:149], v68 offset:464
	ds_read_b128 v[168:171], v69 offset:928
	ds_read_b128 v[172:175], v69 offset:944
	ds_read_b128 v[150:153], v68 offset:480
	ds_read_b128 v[176:179], v69 offset:960
	ds_read_b128 v[180:183], v69 offset:976
	ds_read_b128 v[154:157], v68 offset:496
	ds_read_b128 v[184:187], v69 offset:992
	ds_read_b128 v[188:191], v69 offset:1008
	s_waitcnt lgkmcnt(15)
	v_lshlrev_b32_e32 v126, 16, v70
	v_and_b32_e32 v127, s7, v70
	v_pk_fma_f32 v[86:87], v[94:95], v[126:127], v[86:87]
	v_lshlrev_b32_e32 v128, 16, v71
	v_and_b32_e32 v129, s7, v71
	v_pk_fma_f32 v[192:193], v[96:97], v[128:129], v[192:193]
	v_lshlrev_b32_e32 v130, 16, v72
	v_and_b32_e32 v131, s7, v72
	v_pk_fma_f32 v[194:195], v[98:99], v[130:131], v[194:195]
	v_lshlrev_b32_e32 v132, 16, v73
	v_and_b32_e32 v133, s7, v73
	v_pk_fma_f32 v[204:205], v[100:101], v[132:133], v[204:205]
	s_waitcnt lgkmcnt(15)
	v_lshlrev_b32_e32 v134, 16, v74
	v_and_b32_e32 v135, s7, v74
	v_pk_fma_f32 v[86:87], v[102:103], v[134:135], v[86:87]
	v_lshlrev_b32_e32 v136, 16, v75
	v_and_b32_e32 v137, s7, v75
	v_pk_fma_f32 v[192:193], v[104:105], v[136:137], v[192:193]
	v_lshlrev_b32_e32 v138, 16, v76
	v_and_b32_e32 v139, s7, v76
	v_pk_fma_f32 v[194:195], v[106:107], v[138:139], v[194:195]
	v_lshlrev_b32_e32 v140, 16, v77
	v_and_b32_e32 v141, s7, v77
	v_pk_fma_f32 v[204:205], v[108:109], v[140:141], v[204:205]
	s_waitcnt lgkmcnt(15)
	v_lshlrev_b32_e32 v126, 16, v78
	v_and_b32_e32 v127, s7, v78
	v_pk_fma_f32 v[86:87], v[110:111], v[126:127], v[86:87]
	v_lshlrev_b32_e32 v128, 16, v79
	v_and_b32_e32 v129, s7, v79
	v_pk_fma_f32 v[192:193], v[112:113], v[128:129], v[192:193]
	v_lshlrev_b32_e32 v130, 16, v80
	v_and_b32_e32 v131, s7, v80
	v_pk_fma_f32 v[194:195], v[114:115], v[130:131], v[194:195]
	v_lshlrev_b32_e32 v132, 16, v81
	v_and_b32_e32 v133, s7, v81
	v_pk_fma_f32 v[204:205], v[116:117], v[132:133], v[204:205]
	s_waitcnt lgkmcnt(12)
	v_lshlrev_b32_e32 v134, 16, v82
	v_and_b32_e32 v135, s7, v82
	v_pk_fma_f32 v[86:87], v[118:119], v[134:135], v[86:87]
	v_lshlrev_b32_e32 v136, 16, v83
	v_and_b32_e32 v137, s7, v83
	v_pk_fma_f32 v[192:193], v[120:121], v[136:137], v[192:193]
	v_lshlrev_b32_e32 v138, 16, v84
	v_and_b32_e32 v139, s7, v84
	v_pk_fma_f32 v[194:195], v[122:123], v[138:139], v[194:195]
	v_lshlrev_b32_e32 v140, 16, v85
	v_and_b32_e32 v141, s7, v85
	v_pk_fma_f32 v[204:205], v[124:125], v[140:141], v[204:205]
	s_waitcnt lgkmcnt(9)
	v_lshlrev_b32_e32 v126, 16, v142
	v_and_b32_e32 v127, s7, v142
	v_pk_fma_f32 v[86:87], v[160:161], v[126:127], v[86:87]
	v_lshlrev_b32_e32 v128, 16, v143
	v_and_b32_e32 v129, s7, v143
	v_pk_fma_f32 v[192:193], v[162:163], v[128:129], v[192:193]
	v_lshlrev_b32_e32 v130, 16, v144
	v_and_b32_e32 v131, s7, v144
	v_pk_fma_f32 v[194:195], v[164:165], v[130:131], v[194:195]
	v_lshlrev_b32_e32 v132, 16, v145
	v_and_b32_e32 v133, s7, v145
	v_pk_fma_f32 v[204:205], v[166:167], v[132:133], v[204:205]
	s_waitcnt lgkmcnt(6)
	v_lshlrev_b32_e32 v134, 16, v146
	v_and_b32_e32 v135, s7, v146
	v_pk_fma_f32 v[86:87], v[168:169], v[134:135], v[86:87]
	v_lshlrev_b32_e32 v136, 16, v147
	v_and_b32_e32 v137, s7, v147
	v_pk_fma_f32 v[192:193], v[170:171], v[136:137], v[192:193]
	v_lshlrev_b32_e32 v138, 16, v148
	v_and_b32_e32 v139, s7, v148
	v_pk_fma_f32 v[194:195], v[172:173], v[138:139], v[194:195]
	v_lshlrev_b32_e32 v140, 16, v149
	v_and_b32_e32 v141, s7, v149
	v_pk_fma_f32 v[204:205], v[174:175], v[140:141], v[204:205]
	s_waitcnt lgkmcnt(3)
	v_lshlrev_b32_e32 v126, 16, v150
	v_and_b32_e32 v127, s7, v150
	v_pk_fma_f32 v[86:87], v[176:177], v[126:127], v[86:87]
	v_lshlrev_b32_e32 v128, 16, v151
	v_and_b32_e32 v129, s7, v151
	v_pk_fma_f32 v[192:193], v[178:179], v[128:129], v[192:193]
	v_lshlrev_b32_e32 v130, 16, v152
	v_and_b32_e32 v131, s7, v152
	v_pk_fma_f32 v[194:195], v[180:181], v[130:131], v[194:195]
	v_lshlrev_b32_e32 v132, 16, v153
	v_and_b32_e32 v133, s7, v153
	v_pk_fma_f32 v[204:205], v[182:183], v[132:133], v[204:205]
	s_waitcnt lgkmcnt(0)
	v_lshlrev_b32_e32 v134, 16, v154
	v_and_b32_e32 v135, s7, v154
	v_pk_fma_f32 v[86:87], v[184:185], v[134:135], v[86:87]
	v_lshlrev_b32_e32 v136, 16, v155
	v_and_b32_e32 v137, s7, v155
	v_pk_fma_f32 v[192:193], v[186:187], v[136:137], v[192:193]
	v_lshlrev_b32_e32 v138, 16, v156
	v_and_b32_e32 v139, s7, v156
	v_pk_fma_f32 v[194:195], v[188:189], v[138:139], v[194:195]
	v_lshlrev_b32_e32 v140, 16, v157
	v_and_b32_e32 v141, s7, v157
	v_pk_fma_f32 v[204:205], v[190:191], v[140:141], v[204:205]
	v_pk_add_f32 v[86:87], v[86:87], v[192:193]
	v_pk_add_f32 v[194:195], v[194:195], v[204:205]
	v_pk_add_f32 v[86:87], v[86:87], v[194:195]
	v_add_f32_e32 v60, v86, v87
	v_add_u32_e32 v61, 0x23000, v63
	ds_write_b32 v61, v60
